# grid barrier poll loops: s_sleep removed from the back edge (release noticed one sleep quantum sooner)
# baseline (speedup 1.0000x reference)
; __device__ __forceinline__ unsigned xb_ld(unsigned* p)              { return __hip_atomic_load(p, __ATOMIC_RELAXED, __HIP_MEMORY_SCOPE_AGENT); }
; __device__ __forceinline__ void xcd_barrier_complete(unsigned* bar, unsigned x, unsigned& nloc, unsigned& nx) {
;     ...
;     for (;;) {
;         sum = 0u; cnt = 0u; mine = 0u;
; #pragma unroll
;         for (unsigned j = 0; j < 16; ++j) { const unsigned c = xb_ld(&bar[XB_XCNT(j)]); sum += c; cnt += (c > 0u) ? 1u : 0u; mine = (j == x) ? c : mine; }
;         if (sum == G) break;
;         __builtin_amdgcn_s_sleep(1);
;         if ((++sp & 255u) == 0u) { if (xb_ld(&bar[XB_TMO])) break; if (sp > XB_SPIN_CAP) { atomicAdd(&bar[XB_TMO], 1u); break; } }
;     }
.LBB0_106:
	global_load_dword v15, v16, s[10:11] sc1
	s_waitcnt lgkmcnt(0)
	global_load_dword v0, v16, s[12:13] sc1
	global_load_dword v1, v16, s[14:15] sc1
	global_load_dword v2, v16, s[16:17] sc1
	global_load_dword v3, v16, s[18:19] sc1
	global_load_dword v4, v16, s[24:25] sc1
	global_load_dword v5, v16, s[26:27] sc1
	global_load_dword v6, v16, s[28:29] sc1
	global_load_dword v7, v16, s[30:31] sc1
	global_load_dword v8, v16, s[34:35] sc1
	global_load_dword v9, v16, s[36:37] sc1
	global_load_dword v10, v16, s[38:39] sc1
	global_load_dword v11, v16, s[40:41] sc1
	global_load_dword v12, v16, s[42:43] sc1
	global_load_dword v13, v16, s[44:45] sc1
	global_load_dword v14, v16, s[46:47] sc1
	s_mov_b64 s[48:49], -1
	s_mov_b64 s[50:51], -1
	s_waitcnt vmcnt(14)
	v_add_u32_e32 v17, v0, v15
	s_waitcnt vmcnt(13)
	v_add_u32_e32 v17, v17, v1
	s_waitcnt vmcnt(12)
	v_add_u32_e32 v17, v17, v2
	s_waitcnt vmcnt(11)
	v_add_u32_e32 v17, v17, v3
	s_waitcnt vmcnt(10)
	v_add_u32_e32 v17, v17, v4
	s_waitcnt vmcnt(9)
	v_add_u32_e32 v17, v17, v5
	s_waitcnt vmcnt(8)
	v_add_u32_e32 v17, v17, v6
	s_waitcnt vmcnt(7)
	v_add_u32_e32 v17, v17, v7
	s_waitcnt vmcnt(6)
	v_add_u32_e32 v17, v17, v8
	s_waitcnt vmcnt(5)
	v_add_u32_e32 v17, v17, v9
	s_waitcnt vmcnt(4)
	v_add_u32_e32 v17, v17, v10
	s_waitcnt vmcnt(3)
	v_add_u32_e32 v17, v17, v11
	s_waitcnt vmcnt(2)
	v_add_u32_e32 v17, v17, v12
	s_waitcnt vmcnt(1)
	v_add_u32_e32 v17, v17, v13
	s_waitcnt vmcnt(0)
	v_add_u32_e32 v17, v17, v14
	v_cmp_eq_u32_e32 vcc, s33, v17
	s_cbranch_vccnz .LBB0_105
	s_and_b32 s48, s54, 0xff
	s_cmp_eq_u32 s48, 0
	s_mov_b64 s[48:49], -1
	s_mov_b64 s[52:53], -1
	s_cbranch_scc0 .LBB0_110
	global_load_dword v17, v16, s[8:9] sc1
	s_waitcnt vmcnt(0)
	v_cmp_eq_u32_e32 vcc, 0, v17
	s_cbranch_vccnz .LBB0_112
	s_mov_b64 s[52:53], 0

; __device__ __forceinline__ unsigned xb_ld(unsigned* p)              { return __hip_atomic_load(p, __ATOMIC_RELAXED, __HIP_MEMORY_SCOPE_AGENT); }
; #define XB_SPIN(cond, bar) do { unsigned _sp = 0; while (cond) { __builtin_amdgcn_s_sleep(1); \
;     if ((++_sp & 255u) == 0u) { if (xb_ld(&(bar)[XB_TMO])) break; if (_sp > XB_SPIN_CAP) { atomicAdd(&(bar)[XB_TMO], 1u); break; } } } } while (0)
; __device__ __forceinline__ void xcd_barrier(const XcdBarrier& b) {
;     ...
;             else XB_SPIN(xb_ld(&bar[XB_TOPGEN]) == tg, bar);
.LBB0_124:
	s_and_b32 s28, s3, 0xff
	s_mov_b64 s[26:27], -1
	s_cmp_lg_u32 s28, 0
	s_mov_b64 s[30:31], -1
	s_cbranch_scc1 .LBB0_127
	global_load_dword v2, v0, s[14:15] sc1
	s_waitcnt vmcnt(0)
	v_cmp_eq_u32_e32 vcc, 0, v2
	s_cbranch_vccnz .LBB0_129
	s_mov_b64 s[30:31], 0
	s_mov_b64 s[28:29], -1

; __device__ __forceinline__ unsigned xb_ld(unsigned* p)              { return __hip_atomic_load(p, __ATOMIC_RELAXED, __HIP_MEMORY_SCOPE_AGENT); }
; #define XB_SPIN(cond, bar) do { unsigned _sp = 0; while (cond) { __builtin_amdgcn_s_sleep(1); \
;     if ((++_sp & 255u) == 0u) { if (xb_ld(&(bar)[XB_TMO])) break; if (_sp > XB_SPIN_CAP) { atomicAdd(&(bar)[XB_TMO], 1u); break; } } } } while (0)
; __device__ __forceinline__ void xcd_barrier(const XcdBarrier& b) {
;     ...
;             XB_SPIN(xb_ld(&bar[XB_XGEN(b.x)]) == gen, bar);
.LBB0_141:
	s_and_b32 s24, s3, 0xff
	s_cmp_lg_u32 s24, 0
	s_mov_b64 s[26:27], -1
	s_cbranch_scc1 .LBB0_144
	global_load_dword v1, v0, s[14:15] sc1
	s_waitcnt vmcnt(0)
	v_cmp_eq_u32_e32 vcc, 0, v1
	s_cbranch_vccnz .LBB0_146
	s_mov_b64 s[26:27], 0
	s_mov_b64 s[24:25], -1

; __device__ __forceinline__ unsigned xb_ld(unsigned* p)              { return __hip_atomic_load(p, __ATOMIC_RELAXED, __HIP_MEMORY_SCOPE_AGENT); }
; __device__ __forceinline__ void xcd_barrier_complete(unsigned* bar, unsigned x, unsigned& nloc, unsigned& nx) {
;     ...
;     for (;;) {
;         sum = 0u; cnt = 0u; mine = 0u;
; #pragma unroll
;         for (unsigned j = 0; j < 16; ++j) { const unsigned c = xb_ld(&bar[XB_XCNT(j)]); sum += c; cnt += (c > 0u) ? 1u : 0u; mine = (j == x) ? c : mine; }
;         if (sum == G) break;
;         __builtin_amdgcn_s_sleep(1);
;         if ((++sp & 255u) == 0u) { if (xb_ld(&bar[XB_TMO])) break; if (sp > XB_SPIN_CAP) { atomicAdd(&bar[XB_TMO], 1u); break; } }
;     }
.LBB0_192:
	global_load_dword v15, v97, s[10:11] sc1
	s_waitcnt lgkmcnt(0)
	global_load_dword v0, v97, s[12:13] sc1
	global_load_dword v1, v97, s[14:15] sc1
	global_load_dword v2, v97, s[16:17] sc1
	global_load_dword v3, v97, s[34:35] sc1
	global_load_dword v4, v97, s[52:53] sc1
	global_load_dword v5, v97, s[54:55] sc1
	global_load_dword v6, v97, s[56:57] sc1
	global_load_dword v7, v97, s[60:61] sc1
	global_load_dword v8, v97, s[62:63] sc1
	global_load_dword v9, v97, s[64:65] sc1
	global_load_dword v10, v97, s[66:67] sc1
	global_load_dword v11, v97, s[68:69] sc1
	global_load_dword v12, v97, s[70:71] sc1
	global_load_dword v13, v97, s[72:73] sc1
	global_load_dword v14, v97, s[74:75] sc1
	s_mov_b64 s[76:77], -1
	s_mov_b64 s[78:79], -1
	s_waitcnt vmcnt(14)
	v_add_u32_e32 v16, v0, v15
	s_waitcnt vmcnt(13)
	v_add_u32_e32 v16, v16, v1
	s_waitcnt vmcnt(12)
	v_add_u32_e32 v16, v16, v2
	s_waitcnt vmcnt(11)
	v_add_u32_e32 v16, v16, v3
	s_waitcnt vmcnt(10)
	v_add_u32_e32 v16, v16, v4
	s_waitcnt vmcnt(9)
	v_add_u32_e32 v16, v16, v5
	s_waitcnt vmcnt(8)
	v_add_u32_e32 v16, v16, v6
	s_waitcnt vmcnt(7)
	v_add_u32_e32 v16, v16, v7
	s_waitcnt vmcnt(6)
	v_add_u32_e32 v16, v16, v8
	s_waitcnt vmcnt(5)
	v_add_u32_e32 v16, v16, v9
	s_waitcnt vmcnt(4)
	v_add_u32_e32 v16, v16, v10
	s_waitcnt vmcnt(3)
	v_add_u32_e32 v16, v16, v11
	s_waitcnt vmcnt(2)
	v_add_u32_e32 v16, v16, v12
	s_waitcnt vmcnt(1)
	v_add_u32_e32 v16, v16, v13
	s_waitcnt vmcnt(0)
	v_add_u32_e32 v16, v16, v14
	v_cmp_eq_u32_e32 vcc, s88, v16
	s_cbranch_vccnz .LBB0_191
	s_and_b32 s23, s18, 0xff
	s_cmp_eq_u32 s23, 0
	s_mov_b64 s[80:81], -1
	s_cbranch_scc0 .LBB0_196
	global_load_dword v16, v97, s[8:9] sc1
	s_waitcnt vmcnt(0)
	v_cmp_eq_u32_e32 vcc, 0, v16
	s_cbranch_vccnz .LBB0_198
	s_mov_b64 s[80:81], 0

; __device__ __forceinline__ unsigned xb_ld(unsigned* p)              { return __hip_atomic_load(p, __ATOMIC_RELAXED, __HIP_MEMORY_SCOPE_AGENT); }
; #define XB_SPIN(cond, bar) do { unsigned _sp = 0; while (cond) { __builtin_amdgcn_s_sleep(1); \
;     if ((++_sp & 255u) == 0u) { if (xb_ld(&(bar)[XB_TMO])) break; if (_sp > XB_SPIN_CAP) { atomicAdd(&(bar)[XB_TMO], 1u); break; } } } } while (0)
; __device__ __forceinline__ void xcd_barrier(const XcdBarrier& b) {
;     ...
;             else XB_SPIN(xb_ld(&bar[XB_TOPGEN]) == tg, bar);
.LBB0_210:
	s_and_b32 s18, s3, 0xff
	s_mov_b64 s[54:55], -1
	s_cmp_lg_u32 s18, 0
	s_mov_b64 s[60:61], -1
	s_cbranch_scc1 .LBB0_213
	global_load_dword v0, v97, s[14:15] sc1
	s_waitcnt vmcnt(0)
	v_cmp_eq_u32_e32 vcc, 0, v0
	s_cbranch_vccnz .LBB0_215
	s_mov_b64 s[60:61], 0
	s_mov_b64 s[56:57], -1

; __device__ __forceinline__ unsigned xb_ld(unsigned* p)              { return __hip_atomic_load(p, __ATOMIC_RELAXED, __HIP_MEMORY_SCOPE_AGENT); }
; #define XB_SPIN(cond, bar) do { unsigned _sp = 0; while (cond) { __builtin_amdgcn_s_sleep(1); \
;     if ((++_sp & 255u) == 0u) { if (xb_ld(&(bar)[XB_TMO])) break; if (_sp > XB_SPIN_CAP) { atomicAdd(&(bar)[XB_TMO], 1u); break; } } } } while (0)
; __device__ __forceinline__ void xcd_barrier(const XcdBarrier& b) {
;     ...
;             XB_SPIN(xb_ld(&bar[XB_XGEN(b.x)]) == gen, bar);
.LBB0_227:
	s_and_b32 s18, s3, 0xff
	s_mov_b64 s[52:53], -1
	s_cmp_lg_u32 s18, 0
	s_mov_b64 s[56:57], -1
	s_cbranch_scc1 .LBB0_230
	global_load_dword v0, v97, s[14:15] sc1
	s_waitcnt vmcnt(0)
	v_cmp_eq_u32_e32 vcc, 0, v0
	s_cbranch_vccnz .LBB0_232
	s_mov_b64 s[56:57], 0
	s_mov_b64 s[54:55], -1

; __device__ __forceinline__ unsigned xb_ld(unsigned* p)              { return __hip_atomic_load(p, __ATOMIC_RELAXED, __HIP_MEMORY_SCOPE_AGENT); }
; __device__ __forceinline__ void xcd_barrier_complete(unsigned* bar, unsigned x, unsigned& nloc, unsigned& nx) {
;     ...
;     for (;;) {
;         sum = 0u; cnt = 0u; mine = 0u;
; #pragma unroll
;         for (unsigned j = 0; j < 16; ++j) { const unsigned c = xb_ld(&bar[XB_XCNT(j)]); sum += c; cnt += (c > 0u) ? 1u : 0u; mine = (j == x) ? c : mine; }
;         if (sum == G) break;
;         __builtin_amdgcn_s_sleep(1);
;         if ((++sp & 255u) == 0u) { if (xb_ld(&bar[XB_TMO])) break; if (sp > XB_SPIN_CAP) { atomicAdd(&bar[XB_TMO], 1u); break; } }
;     }
.LBB0_292:
	global_load_dword v15, v97, s[10:11] sc1
	s_waitcnt lgkmcnt(0)
	global_load_dword v0, v97, s[12:13] sc1
	global_load_dword v1, v97, s[14:15] sc1
	global_load_dword v2, v97, s[16:17] sc1
	global_load_dword v3, v97, s[34:35] sc1
	global_load_dword v4, v97, s[52:53] sc1
	global_load_dword v5, v97, s[54:55] sc1
	global_load_dword v6, v97, s[56:57] sc1
	global_load_dword v7, v97, s[60:61] sc1
	global_load_dword v8, v97, s[62:63] sc1
	global_load_dword v9, v97, s[64:65] sc1
	global_load_dword v10, v97, s[66:67] sc1
	global_load_dword v11, v97, s[68:69] sc1
	global_load_dword v12, v97, s[70:71] sc1
	global_load_dword v13, v97, s[72:73] sc1
	global_load_dword v14, v97, s[74:75] sc1
	s_mov_b64 s[76:77], -1
	s_mov_b64 s[78:79], -1
	s_waitcnt vmcnt(14)
	v_add_u32_e32 v16, v0, v15
	s_waitcnt vmcnt(13)
	v_add_u32_e32 v16, v16, v1
	s_waitcnt vmcnt(12)
	v_add_u32_e32 v16, v16, v2
	s_waitcnt vmcnt(11)
	v_add_u32_e32 v16, v16, v3
	s_waitcnt vmcnt(10)
	v_add_u32_e32 v16, v16, v4
	s_waitcnt vmcnt(9)
	v_add_u32_e32 v16, v16, v5
	s_waitcnt vmcnt(8)
	v_add_u32_e32 v16, v16, v6
	s_waitcnt vmcnt(7)
	v_add_u32_e32 v16, v16, v7
	s_waitcnt vmcnt(6)
	v_add_u32_e32 v16, v16, v8
	s_waitcnt vmcnt(5)
	v_add_u32_e32 v16, v16, v9
	s_waitcnt vmcnt(4)
	v_add_u32_e32 v16, v16, v10
	s_waitcnt vmcnt(3)
	v_add_u32_e32 v16, v16, v11
	s_waitcnt vmcnt(2)
	v_add_u32_e32 v16, v16, v12
	s_waitcnt vmcnt(1)
	v_add_u32_e32 v16, v16, v13
	s_waitcnt vmcnt(0)
	v_add_u32_e32 v16, v16, v14
	v_cmp_eq_u32_e32 vcc, s88, v16
	s_cbranch_vccnz .LBB0_291
	s_and_b32 s18, s3, 0xff
	s_cmp_eq_u32 s18, 0
	s_mov_b64 s[80:81], -1
	s_cbranch_scc0 .LBB0_296
	global_load_dword v16, v97, s[8:9] sc1
	s_waitcnt vmcnt(0)
	v_cmp_eq_u32_e32 vcc, 0, v16
	s_cbranch_vccnz .LBB0_298
	s_mov_b64 s[80:81], 0

; __device__ __forceinline__ unsigned xb_ld(unsigned* p)              { return __hip_atomic_load(p, __ATOMIC_RELAXED, __HIP_MEMORY_SCOPE_AGENT); }
; #define XB_SPIN(cond, bar) do { unsigned _sp = 0; while (cond) { __builtin_amdgcn_s_sleep(1); \
;     if ((++_sp & 255u) == 0u) { if (xb_ld(&(bar)[XB_TMO])) break; if (_sp > XB_SPIN_CAP) { atomicAdd(&(bar)[XB_TMO], 1u); break; } } } } while (0)
; __device__ __forceinline__ void xcd_barrier(const XcdBarrier& b) {
;     ...
;             else XB_SPIN(xb_ld(&bar[XB_TOPGEN]) == tg, bar);
.LBB0_310:
	s_and_b32 s3, s2, 0xff
	s_mov_b64 s[54:55], -1
	s_cmp_lg_u32 s3, 0
	s_mov_b64 s[60:61], -1
	s_cbranch_scc1 .LBB0_313
	global_load_dword v0, v97, s[14:15] sc1
	s_waitcnt vmcnt(0)
	v_cmp_eq_u32_e32 vcc, 0, v0
	s_cbranch_vccnz .LBB0_315
	s_mov_b64 s[60:61], 0
	s_mov_b64 s[56:57], -1

; __device__ __forceinline__ unsigned xb_ld(unsigned* p)              { return __hip_atomic_load(p, __ATOMIC_RELAXED, __HIP_MEMORY_SCOPE_AGENT); }
; #define XB_SPIN(cond, bar) do { unsigned _sp = 0; while (cond) { __builtin_amdgcn_s_sleep(1); \
;     if ((++_sp & 255u) == 0u) { if (xb_ld(&(bar)[XB_TMO])) break; if (_sp > XB_SPIN_CAP) { atomicAdd(&(bar)[XB_TMO], 1u); break; } } } } while (0)
; __device__ __forceinline__ void xcd_barrier(const XcdBarrier& b) {
;     ...
;             XB_SPIN(xb_ld(&bar[XB_XGEN(b.x)]) == gen, bar);
.LBB0_327:
	s_and_b32 s3, s2, 0xff
	s_mov_b64 s[52:53], -1
	s_cmp_lg_u32 s3, 0
	s_mov_b64 s[56:57], -1
	s_cbranch_scc1 .LBB0_330
	global_load_dword v0, v97, s[14:15] sc1
	s_waitcnt vmcnt(0)
	v_cmp_eq_u32_e32 vcc, 0, v0
	s_cbranch_vccnz .LBB0_332
	s_mov_b64 s[56:57], 0
	s_mov_b64 s[54:55], -1

; __device__ __forceinline__ unsigned xb_ld(unsigned* p)              { return __hip_atomic_load(p, __ATOMIC_RELAXED, __HIP_MEMORY_SCOPE_AGENT); }
; __device__ __forceinline__ void xcd_barrier_complete(unsigned* bar, unsigned x, unsigned& nloc, unsigned& nx) {
;     ...
;     for (;;) {
;         sum = 0u; cnt = 0u; mine = 0u;
; #pragma unroll
;         for (unsigned j = 0; j < 16; ++j) { const unsigned c = xb_ld(&bar[XB_XCNT(j)]); sum += c; cnt += (c > 0u) ? 1u : 0u; mine = (j == x) ? c : mine; }
;         if (sum == G) break;
;         __builtin_amdgcn_s_sleep(1);
;         if ((++sp & 255u) == 0u) { if (xb_ld(&bar[XB_TMO])) break; if (sp > XB_SPIN_CAP) { atomicAdd(&bar[XB_TMO], 1u); break; } }
;     }
.LBB0_658:
	global_load_dword v15, v97, s[10:11] sc1
	s_waitcnt lgkmcnt(0)
	global_load_dword v0, v97, s[14:15] sc1
	global_load_dword v1, v97, s[16:17] sc1
	global_load_dword v2, v97, s[34:35] sc1
	global_load_dword v3, v97, s[52:53] sc1
	global_load_dword v4, v97, s[54:55] sc1
	global_load_dword v5, v97, s[56:57] sc1
	global_load_dword v6, v97, s[60:61] sc1
	global_load_dword v7, v97, s[62:63] sc1
	global_load_dword v8, v97, s[64:65] sc1
	global_load_dword v9, v97, s[66:67] sc1
	global_load_dword v10, v97, s[68:69] sc1
	global_load_dword v11, v97, s[70:71] sc1
	global_load_dword v12, v97, s[72:73] sc1
	global_load_dword v13, v97, s[74:75] sc1
	global_load_dword v14, v97, s[76:77] sc1
	s_mov_b64 s[78:79], -1
	s_mov_b64 s[80:81], -1
	s_waitcnt vmcnt(14)
	v_add_u32_e32 v16, v0, v15
	s_waitcnt vmcnt(13)
	v_add_u32_e32 v16, v16, v1
	s_waitcnt vmcnt(12)
	v_add_u32_e32 v16, v16, v2
	s_waitcnt vmcnt(11)
	v_add_u32_e32 v16, v16, v3
	s_waitcnt vmcnt(10)
	v_add_u32_e32 v16, v16, v4
	s_waitcnt vmcnt(9)
	v_add_u32_e32 v16, v16, v5
	s_waitcnt vmcnt(8)
	v_add_u32_e32 v16, v16, v6
	s_waitcnt vmcnt(7)
	v_add_u32_e32 v16, v16, v7
	s_waitcnt vmcnt(6)
	v_add_u32_e32 v16, v16, v8
	s_waitcnt vmcnt(5)
	v_add_u32_e32 v16, v16, v9
	s_waitcnt vmcnt(4)
	v_add_u32_e32 v16, v16, v10
	s_waitcnt vmcnt(3)
	v_add_u32_e32 v16, v16, v11
	s_waitcnt vmcnt(2)
	v_add_u32_e32 v16, v16, v12
	s_waitcnt vmcnt(1)
	v_add_u32_e32 v16, v16, v13
	s_waitcnt vmcnt(0)
	v_add_u32_e32 v16, v16, v14
	v_cmp_eq_u32_e32 vcc, s88, v16
	s_cbranch_vccnz .LBB0_657
	s_and_b32 s23, s18, 0xff
	s_cmp_eq_u32 s23, 0
	s_mov_b64 s[82:83], -1
	s_cbranch_scc0 .LBB0_662
	global_load_dword v16, v97, s[8:9] sc1
	s_waitcnt vmcnt(0)
	v_cmp_eq_u32_e32 vcc, 0, v16
	s_cbranch_vccnz .LBB0_664
	s_mov_b64 s[82:83], 0

; __device__ __forceinline__ unsigned xb_ld(unsigned* p)              { return __hip_atomic_load(p, __ATOMIC_RELAXED, __HIP_MEMORY_SCOPE_AGENT); }
; #define XB_SPIN(cond, bar) do { unsigned _sp = 0; while (cond) { __builtin_amdgcn_s_sleep(1); \
;     if ((++_sp & 255u) == 0u) { if (xb_ld(&(bar)[XB_TMO])) break; if (_sp > XB_SPIN_CAP) { atomicAdd(&(bar)[XB_TMO], 1u); break; } } } } while (0)
; __device__ __forceinline__ void xcd_barrier(const XcdBarrier& b) {
;     ...
;             else XB_SPIN(xb_ld(&bar[XB_TOPGEN]) == tg, bar);
.LBB0_676:
	s_and_b32 s18, s3, 0xff
	s_mov_b64 s[56:57], -1
	s_cmp_lg_u32 s18, 0
	s_mov_b64 s[62:63], -1
	s_cbranch_scc1 .LBB0_679
	global_load_dword v0, v97, s[16:17] sc1
	s_waitcnt vmcnt(0)
	v_cmp_eq_u32_e32 vcc, 0, v0
	s_cbranch_vccnz .LBB0_681
	s_mov_b64 s[62:63], 0
	s_mov_b64 s[60:61], -1

; __device__ __forceinline__ unsigned xb_ld(unsigned* p)              { return __hip_atomic_load(p, __ATOMIC_RELAXED, __HIP_MEMORY_SCOPE_AGENT); }
; #define XB_SPIN(cond, bar) do { unsigned _sp = 0; while (cond) { __builtin_amdgcn_s_sleep(1); \
;     if ((++_sp & 255u) == 0u) { if (xb_ld(&(bar)[XB_TMO])) break; if (_sp > XB_SPIN_CAP) { atomicAdd(&(bar)[XB_TMO], 1u); break; } } } } while (0)
; __device__ __forceinline__ void xcd_barrier(const XcdBarrier& b) {
;     ...
;             XB_SPIN(xb_ld(&bar[XB_XGEN(b.x)]) == gen, bar);
.LBB0_710:
	s_and_b32 s18, s3, 0xff
	s_mov_b64 s[54:55], -1
	s_cmp_lg_u32 s18, 0
	s_mov_b64 s[60:61], -1
	s_cbranch_scc1 .LBB0_713
	global_load_dword v0, v97, s[16:17] sc1
	s_waitcnt vmcnt(0)
	v_cmp_eq_u32_e32 vcc, 0, v0
	s_cbranch_vccnz .LBB0_715
	s_mov_b64 s[60:61], 0
	s_mov_b64 s[56:57], -1

; __device__ __forceinline__ unsigned xb_ld(unsigned* p)              { return __hip_atomic_load(p, __ATOMIC_RELAXED, __HIP_MEMORY_SCOPE_AGENT); }
; __device__ __forceinline__ void xcd_barrier_complete(unsigned* bar, unsigned x, unsigned& nloc, unsigned& nx) {
;     ...
;     for (;;) {
;         sum = 0u; cnt = 0u; mine = 0u;
; #pragma unroll
;         for (unsigned j = 0; j < 16; ++j) { const unsigned c = xb_ld(&bar[XB_XCNT(j)]); sum += c; cnt += (c > 0u) ? 1u : 0u; mine = (j == x) ? c : mine; }
;         if (sum == G) break;
;         __builtin_amdgcn_s_sleep(1);
;         if ((++sp & 255u) == 0u) { if (xb_ld(&bar[XB_TMO])) break; if (sp > XB_SPIN_CAP) { atomicAdd(&bar[XB_TMO], 1u); break; } }
;     }
.LBB0_1226:
	global_load_dword v15, v97, s[10:11] sc1
	s_waitcnt lgkmcnt(0)
	global_load_dword v0, v97, s[12:13] sc1
	global_load_dword v1, v97, s[14:15] sc1
	global_load_dword v2, v97, s[16:17] sc1
	global_load_dword v3, v97, s[34:35] sc1
	global_load_dword v4, v97, s[52:53] sc1
	global_load_dword v5, v97, s[54:55] sc1
	global_load_dword v6, v97, s[56:57] sc1
	global_load_dword v7, v97, s[58:59] sc1
	global_load_dword v8, v97, s[60:61] sc1
	global_load_dword v9, v97, s[62:63] sc1
	global_load_dword v10, v97, s[64:65] sc1
	global_load_dword v11, v97, s[66:67] sc1
	global_load_dword v12, v97, s[68:69] sc1
	global_load_dword v13, v97, s[70:71] sc1
	global_load_dword v14, v97, s[72:73] sc1
	s_mov_b64 s[74:75], -1
	s_mov_b64 s[76:77], -1
	s_waitcnt vmcnt(14)
	v_add_u32_e32 v16, v0, v15
	s_waitcnt vmcnt(13)
	v_add_u32_e32 v16, v16, v1
	s_waitcnt vmcnt(12)
	v_add_u32_e32 v16, v16, v2
	s_waitcnt vmcnt(11)
	v_add_u32_e32 v16, v16, v3
	s_waitcnt vmcnt(10)
	v_add_u32_e32 v16, v16, v4
	s_waitcnt vmcnt(9)
	v_add_u32_e32 v16, v16, v5
	s_waitcnt vmcnt(8)
	v_add_u32_e32 v16, v16, v6
	s_waitcnt vmcnt(7)
	v_add_u32_e32 v16, v16, v7
	s_waitcnt vmcnt(6)
	v_add_u32_e32 v16, v16, v8
	s_waitcnt vmcnt(5)
	v_add_u32_e32 v16, v16, v9
	s_waitcnt vmcnt(4)
	v_add_u32_e32 v16, v16, v10
	s_waitcnt vmcnt(3)
	v_add_u32_e32 v16, v16, v11
	s_waitcnt vmcnt(2)
	v_add_u32_e32 v16, v16, v12
	s_waitcnt vmcnt(1)
	v_add_u32_e32 v16, v16, v13
	s_waitcnt vmcnt(0)
	v_add_u32_e32 v16, v16, v14
	v_cmp_eq_u32_e32 vcc, s88, v16
	s_cbranch_vccnz .LBB0_1225
	s_and_b32 s23, s18, 0xff
	s_cmp_eq_u32 s23, 0
	s_mov_b64 s[78:79], -1
	s_cbranch_scc0 .LBB0_1230
	global_load_dword v16, v97, s[8:9] sc1
	s_waitcnt vmcnt(0)
	v_cmp_eq_u32_e32 vcc, 0, v16
	s_cbranch_vccnz .LBB0_1232
	s_mov_b64 s[78:79], 0

; __device__ __forceinline__ unsigned xb_ld(unsigned* p)              { return __hip_atomic_load(p, __ATOMIC_RELAXED, __HIP_MEMORY_SCOPE_AGENT); }
; #define XB_SPIN(cond, bar) do { unsigned _sp = 0; while (cond) { __builtin_amdgcn_s_sleep(1); \
;     if ((++_sp & 255u) == 0u) { if (xb_ld(&(bar)[XB_TMO])) break; if (_sp > XB_SPIN_CAP) { atomicAdd(&(bar)[XB_TMO], 1u); break; } } } } while (0)
; __device__ __forceinline__ void xcd_barrier(const XcdBarrier& b) {
;     ...
;             else XB_SPIN(xb_ld(&bar[XB_TOPGEN]) == tg, bar);
.LBB0_1244:
	s_and_b32 s18, s3, 0xff
	s_mov_b64 s[54:55], -1
	s_cmp_lg_u32 s18, 0
	s_mov_b64 s[58:59], -1
	s_cbranch_scc1 .LBB0_1247
	global_load_dword v0, v97, s[14:15] sc1
	s_waitcnt vmcnt(0)
	v_cmp_eq_u32_e32 vcc, 0, v0
	s_cbranch_vccnz .LBB0_1249
	s_mov_b64 s[58:59], 0
	s_mov_b64 s[56:57], -1

; __device__ __forceinline__ unsigned xb_ld(unsigned* p)              { return __hip_atomic_load(p, __ATOMIC_RELAXED, __HIP_MEMORY_SCOPE_AGENT); }
; __device__ __forceinline__ void xcd_barrier_complete(unsigned* bar, unsigned x, unsigned& nloc, unsigned& nx) {
;     ...
;     for (;;) {
;         sum = 0u; cnt = 0u; mine = 0u;
; #pragma unroll
;         for (unsigned j = 0; j < 16; ++j) { const unsigned c = xb_ld(&bar[XB_XCNT(j)]); sum += c; cnt += (c > 0u) ? 1u : 0u; mine = (j == x) ? c : mine; }
;         if (sum == G) break;
;         __builtin_amdgcn_s_sleep(1);
;         if ((++sp & 255u) == 0u) { if (xb_ld(&bar[XB_TMO])) break; if (sp > XB_SPIN_CAP) { atomicAdd(&bar[XB_TMO], 1u); break; } }
;     }
.LBB0_1444:
	global_load_dword v15, v97, s[10:11] sc1
	s_waitcnt lgkmcnt(0)
	global_load_dword v0, v97, s[12:13] sc1
	global_load_dword v1, v97, s[14:15] sc1
	global_load_dword v2, v97, s[16:17] sc1
	global_load_dword v3, v97, s[34:35] sc1
	global_load_dword v4, v97, s[52:53] sc1
	global_load_dword v5, v97, s[54:55] sc1
	global_load_dword v6, v97, s[56:57] sc1
	global_load_dword v7, v97, s[58:59] sc1
	global_load_dword v8, v97, s[60:61] sc1
	global_load_dword v9, v97, s[62:63] sc1
	global_load_dword v10, v97, s[64:65] sc1
	global_load_dword v11, v97, s[66:67] sc1
	global_load_dword v12, v97, s[68:69] sc1
	global_load_dword v13, v97, s[70:71] sc1
	global_load_dword v14, v97, s[72:73] sc1
	s_mov_b64 s[74:75], -1
	s_mov_b64 s[76:77], -1
	s_waitcnt vmcnt(14)
	v_add_u32_e32 v16, v0, v15
	s_waitcnt vmcnt(13)
	v_add_u32_e32 v16, v16, v1
	s_waitcnt vmcnt(12)
	v_add_u32_e32 v16, v16, v2
	s_waitcnt vmcnt(11)
	v_add_u32_e32 v16, v16, v3
	s_waitcnt vmcnt(10)
	v_add_u32_e32 v16, v16, v4
	s_waitcnt vmcnt(9)
	v_add_u32_e32 v16, v16, v5
	s_waitcnt vmcnt(8)
	v_add_u32_e32 v16, v16, v6
	s_waitcnt vmcnt(7)
	v_add_u32_e32 v16, v16, v7
	s_waitcnt vmcnt(6)
	v_add_u32_e32 v16, v16, v8
	s_waitcnt vmcnt(5)
	v_add_u32_e32 v16, v16, v9
	s_waitcnt vmcnt(4)
	v_add_u32_e32 v16, v16, v10
	s_waitcnt vmcnt(3)
	v_add_u32_e32 v16, v16, v11
	s_waitcnt vmcnt(2)
	v_add_u32_e32 v16, v16, v12
	s_waitcnt vmcnt(1)
	v_add_u32_e32 v16, v16, v13
	s_waitcnt vmcnt(0)
	v_add_u32_e32 v16, v16, v14
	v_cmp_eq_u32_e32 vcc, s88, v16
	s_cbranch_vccnz .LBB0_1443
	s_and_b32 s18, s3, 0xff
	s_cmp_eq_u32 s18, 0
	s_mov_b64 s[78:79], -1
	s_cbranch_scc0 .LBB0_1448
	global_load_dword v16, v97, s[8:9] sc1
	s_waitcnt vmcnt(0)
	v_cmp_eq_u32_e32 vcc, 0, v16
	s_cbranch_vccnz .LBB0_1450
	s_mov_b64 s[78:79], 0

; __device__ __forceinline__ unsigned xb_ld(unsigned* p)              { return __hip_atomic_load(p, __ATOMIC_RELAXED, __HIP_MEMORY_SCOPE_AGENT); }
; #define XB_SPIN(cond, bar) do { unsigned _sp = 0; while (cond) { __builtin_amdgcn_s_sleep(1); \
;     if ((++_sp & 255u) == 0u) { if (xb_ld(&(bar)[XB_TMO])) break; if (_sp > XB_SPIN_CAP) { atomicAdd(&(bar)[XB_TMO], 1u); break; } } } } while (0)
; __device__ __forceinline__ void xcd_barrier(const XcdBarrier& b) {
;     ...
;             XB_SPIN(xb_ld(&bar[XB_XGEN(b.x)]) == gen, bar);
.LBB0_1462:
	s_and_b32 s3, s2, 0xff
	s_mov_b64 s[54:55], -1
	s_cmp_lg_u32 s3, 0
	s_mov_b64 s[58:59], -1
	s_cbranch_scc1 .LBB0_1465
	global_load_dword v0, v97, s[14:15] sc1
	s_waitcnt vmcnt(0)
	v_cmp_eq_u32_e32 vcc, 0, v0
	s_cbranch_vccnz .LBB0_1467
	s_mov_b64 s[58:59], 0
	s_mov_b64 s[56:57], -1
